# conv weights-before-prefetch counted vmcnt; DN/SSD loop-top store drains relaxed; nt on P7 XB stores
# speedup vs baseline: 1.0006x; 1.0006x over previous
; __device__ __forceinline__ float wave_sum(float v) { return lane63(wave_scan_incl(v)); }
; template <bool XSRC_BF, bool XDST_BF> ...
;     ...
;         const int b = seq_of_row(row);
;         float xv[4][8]; vu4 hraw[4];
; #pragma unroll
;         for (int j = 0; j < 4; ++j) { if (XSRC_BF) unpack8(nxb[j], xv[j]); else {
; #pragma unroll
;                 for (int e = 0; e < 8; ++e) xv[j][e] = nxf[j][e]; }
;             hraw[j] = nho[j]; }
;         rown = it + 1 < niter ? ROW_OF(it + 1) : -1;
;         if (rown >= 0) ROW_LOAD(rown)
;         if (ho) {
;             float hv[4][8]; float ss = 0.f;
; #pragma unroll
;             for (int j = 0; j < 4; ++j) { unpack8(hraw[j], hv[j]);
; #pragma unroll
;                 for (int e = 0; e < 8; ++e) ss += hv[j][e] * hv[j][e]; }
;             ss = wave_sum(ss);
;             const float r1 = rsqrtf(ss * (1.0f / DM) + EPSN);
; #pragma unroll
;             for (int j = 0; j < 4; ++j) { float gt[8]; load8f(mgate + (size_t)b * 12288 + 8 * lane + 512 * j, gt);
; #pragma unroll
;                 for (int e = 0; e < 8; ++e) xv[j][e] += gt[e] * (hv[j][e] * r1); }
;         }
.LBB0_870:
	v_sub_co_u32_e32 v100, vcc, s24, v99
	s_nop 0
	v_readfirstlane_b32 s25, v100
	s_lshr_b32 s25, s25, 12
	s_add_i32 s25, s25, 4
	s_lshr_b32 s34, s24, 13
	s_and_b64 s[30:31], vcc, exec
	s_cselect_b32 s25, s34, s25
	v_mad_u64_u32 v[136:137], s[30:31], s25, v118, v[104:105]
	global_load_dwordx4 v[110:113], v[136:137], off offset:16
	global_load_dwordx4 v[114:117], v[136:137], off
	global_load_dwordx4 v[120:123], v[136:137], off offset:2064
	global_load_dwordx4 v[124:127], v[136:137], off offset:2048
	v_add_co_u32_e32 v138, vcc, s43, v136
	v_lshl_add_u64 v[132:133], v[136:137], 0, s[8:9]
	s_nop 0
	v_addc_co_u32_e32 v139, vcc, 0, v137, vcc
	global_load_dwordx4 v[128:131], v[138:139], off
	s_nop 0
	global_load_dwordx4 v[132:135], v[132:133], off offset:16
	v_lshl_add_u64 v[140:141], v[136:137], 0, s[10:11]
	global_load_dwordx4 v[136:139], v[138:139], off offset:2048
	s_nop 0
	global_load_dwordx4 v[140:143], v[140:141], off offset:16
	v_lshlrev_b32_e32 v190, 16, v66
	v_and_b32_e32 v191, 0xffff0000, v66
	v_lshlrev_b32_e32 v186, 16, v67
	v_and_b32_e32 v187, 0xffff0000, v67
	v_pk_mul_f32 v[66:67], v[190:191], v[190:191]
	v_pk_mul_f32 v[188:189], v[186:187], v[186:187]
	v_add_f32_e32 v66, v66, v67
	v_lshlrev_b32_e32 v184, 16, v68
	v_and_b32_e32 v185, 0xffff0000, v68
	v_add_f32_e32 v66, v188, v66
	v_lshlrev_b32_e32 v180, 16, v69
	v_and_b32_e32 v181, 0xffff0000, v69
	v_pk_mul_f32 v[68:69], v[184:185], v[184:185]
	v_add_f32_e32 v66, v189, v66
	v_add_f32_e32 v66, v68, v66
	v_pk_mul_f32 v[182:183], v[180:181], v[180:181]
	v_add_f32_e32 v66, v69, v66
	v_lshlrev_b32_e32 v178, 16, v78
	v_and_b32_e32 v179, 0xffff0000, v78
	v_add_f32_e32 v66, v182, v66
	v_lshlrev_b32_e32 v174, 16, v79
	v_and_b32_e32 v175, 0xffff0000, v79
	v_pk_mul_f32 v[78:79], v[178:179], v[178:179]
	v_add_f32_e32 v66, v183, v66
	v_add_f32_e32 v66, v78, v66
	v_pk_mul_f32 v[176:177], v[174:175], v[174:175]
	v_add_f32_e32 v66, v79, v66
	v_lshlrev_b32_e32 v172, 16, v80
	v_and_b32_e32 v173, 0xffff0000, v80
	v_add_f32_e32 v66, v176, v66
	v_lshlrev_b32_e32 v168, 16, v81
	v_and_b32_e32 v169, 0xffff0000, v81
	v_pk_mul_f32 v[80:81], v[172:173], v[172:173]
	v_add_f32_e32 v66, v177, v66
	v_add_f32_e32 v66, v80, v66
	v_pk_mul_f32 v[170:171], v[168:169], v[168:169]
	v_add_f32_e32 v66, v81, v66
	v_lshlrev_b32_e32 v166, 16, v90
	v_and_b32_e32 v167, 0xffff0000, v90
	v_add_f32_e32 v66, v170, v66
	v_lshlrev_b32_e32 v162, 16, v91
	v_and_b32_e32 v163, 0xffff0000, v91
	v_pk_mul_f32 v[90:91], v[166:167], v[166:167]
	v_add_f32_e32 v66, v171, v66
	v_add_f32_e32 v66, v90, v66
	v_pk_mul_f32 v[164:165], v[162:163], v[162:163]
	v_add_f32_e32 v66, v91, v66
	v_lshlrev_b32_e32 v160, 16, v92
	v_and_b32_e32 v161, 0xffff0000, v92
	v_add_f32_e32 v66, v164, v66
	v_lshlrev_b32_e32 v156, 16, v93
	v_and_b32_e32 v157, 0xffff0000, v93
	v_pk_mul_f32 v[92:93], v[160:161], v[160:161]
	v_add_f32_e32 v66, v165, v66
	v_add_f32_e32 v66, v92, v66
	v_pk_mul_f32 v[158:159], v[156:157], v[156:157]
	v_add_f32_e32 v66, v93, v66
	v_lshlrev_b32_e32 v154, 16, v94
	v_and_b32_e32 v155, 0xffff0000, v94
	v_add_f32_e32 v66, v158, v66
	v_lshlrev_b32_e32 v150, 16, v95
	v_and_b32_e32 v151, 0xffff0000, v95
	v_pk_mul_f32 v[94:95], v[154:155], v[154:155]
	v_add_f32_e32 v66, v159, v66
	v_add_f32_e32 v66, v94, v66
	v_pk_mul_f32 v[152:153], v[150:151], v[150:151]
	v_add_f32_e32 v66, v95, v66
	v_lshlrev_b32_e32 v148, 16, v96
	v_and_b32_e32 v149, 0xffff0000, v96
	v_add_f32_e32 v66, v152, v66
	v_lshlrev_b32_e32 v144, 16, v97
	v_and_b32_e32 v145, 0xffff0000, v97
	v_pk_mul_f32 v[96:97], v[148:149], v[148:149]
	v_add_f32_e32 v66, v153, v66
	v_add_f32_e32 v66, v96, v66
	v_pk_mul_f32 v[146:147], v[144:145], v[144:145]
	v_add_f32_e32 v66, v97, v66
	v_add_f32_e32 v66, v146, v66
	v_add_f32_e32 v66, v147, v66
	v_mov_b32_e32 v67, v101
	s_mul_hi_u32 s31, s25, 0xc000
	v_add_f32_dpp v66, v66, v66 row_shr:1 row_mask:0xf bank_mask:0xf bound_ctrl:1
	v_lshlrev_b32_e32 v100, 2, v98
	s_nop 0
	v_add_f32_dpp v66, v66, v66 row_shr:2 row_mask:0xf bank_mask:0xf bound_ctrl:1
	s_nop 1
	v_add_f32_dpp v66, v66, v66 row_shr:4 row_mask:0xf bank_mask:0xf bound_ctrl:1
	s_nop 1
	v_add_f32_dpp v66, v66, v66 row_shr:8 row_mask:0xf bank_mask:0xf bound_ctrl:1
	s_nop 1
	v_mov_b32_dpp v67, v66 row_bcast:15 row_mask:0xa bank_mask:0xf
	v_add_f32_e32 v66, v66, v67
	v_mov_b32_e32 v67, v101
	s_nop 1
	v_mov_b32_dpp v67, v66 row_bcast:31 row_mask:0xc bank_mask:0xf
	v_add_f32_e32 v66, v66, v67
	s_nop 0
	v_readlane_b32 s30, v66, 63
	s_nop 1
	v_fma_f32 v66, s30, v119, v1
	v_mul_f32_e32 v67, 0x4b800000, v66
	v_cmp_gt_f32_e32 vcc, s44, v66
	s_mul_i32 s30, s25, 0xc000
	s_mov_b32 s25, s7
	v_cndmask_b32_e32 v66, v66, v67, vcc
	v_rsq_f32_e32 v66, v66
	s_lshl_b64 s[24:25], s[24:25], 12
	s_add_u32 s30, s38, s30
	s_addc_u32 s31, s39, s31
	v_mul_f32_e32 v67, 0x45800000, v66
	v_cndmask_b32_e32 v66, v66, v67, vcc
	v_pk_mul_f32 v[68:69], v[66:67], v[190:191] op_sel_hi:[0,1]
	s_waitcnt vmcnt(6)
	v_pk_fma_f32 v[68:69], v[114:115], v[68:69], v[22:23]
	v_pk_mul_f32 v[22:23], v[66:67], v[186:187] op_sel_hi:[0,1]
	v_pk_fma_f32 v[78:79], v[116:117], v[22:23], v[24:25]
	v_pk_mul_f32 v[22:23], v[66:67], v[184:185] op_sel_hi:[0,1]
	v_pk_fma_f32 v[80:81], v[110:111], v[22:23], v[6:7]
	v_pk_mul_f32 v[6:7], v[66:67], v[180:181] op_sel_hi:[0,1]
	v_pk_fma_f32 v[90:91], v[112:113], v[6:7], v[8:9]
	v_pk_mul_f32 v[6:7], v[66:67], v[178:179] op_sel_hi:[0,1]
	s_waitcnt vmcnt(4)
	v_pk_fma_f32 v[22:23], v[124:125], v[6:7], v[18:19]
	v_pk_mul_f32 v[6:7], v[66:67], v[174:175] op_sel_hi:[0,1]
	v_pk_fma_f32 v[24:25], v[126:127], v[6:7], v[20:21]
	v_pk_mul_f32 v[6:7], v[66:67], v[172:173] op_sel_hi:[0,1]
	v_pk_fma_f32 v[18:19], v[120:121], v[6:7], v[2:3]
	v_pk_mul_f32 v[6:7], v[66:67], v[160:161] op_sel_hi:[0,1]
	s_waitcnt vmcnt(2)
; __device__ __forceinline__ vu4 pack8(const float (&f)[8]) { vu4 w; w.x = pg8::cvt_pk_bf16(f[0], f[1]); w.y = pg8::cvt_pk_bf16(f[2], f[3]); w.z = pg8::cvt_pk_bf16(f[4], f[5]); w.w = pg8::cvt_pk_bf16(f[6], f[7]); return w; }
; __device__ __forceinline__ float wave_sum(float v) { return lane63(wave_scan_incl(v)); }
; template <bool XSRC_BF, bool XDST_BF> ...
;     ...
;             for (int j = 0; j < 4; ++j) { float gt[8]; load8f(mgate + (size_t)b * 12288 + 8 * lane + 512 * j, gt);
; #pragma unroll
;                 for (int e = 0; e < 8; ++e) xv[j][e] += gt[e] * (hv[j][e] * r1); }
;         }
;         if (x_dst) {
; #pragma unroll
;             for (int j = 0; j < 4; ++j) { if (XDST_BF) *(vu4*)((bf16_t*)x_dst + (size_t)row * DM + 8 * lane + 512 * j) = pack8(xv[j]); else store8f(x_dst + (size_t)row * DM + 8 * lane + 512 * j, xv[j]); }
;         }
;         if (h || ug) {
;             float ss = 0.f;
; #pragma unroll
;             for (int j = 0; j < 4; ++j)
; #pragma unroll
;                 for (int e = 0; e < 8; ++e) ss += xv[j][e] * xv[j][e];
;             ss = wave_sum(ss);
;             const float r2 = rsqrtf(ss * (1.0f / DM) + EPSN);
	v_pk_fma_f32 v[6:7], v[132:133], v[6:7], v[42:43]
	v_pk_mul_f32 v[42:43], v[66:67], v[154:155] op_sel_hi:[0,1]
	s_waitcnt vmcnt(1)
	v_pk_fma_f32 v[110:111], v[136:137], v[42:43], v[54:55]
	v_pk_mul_f32 v[42:43], v[66:67], v[150:151] op_sel_hi:[0,1]
	v_pk_mul_f32 v[2:3], v[66:67], v[168:169] op_sel_hi:[0,1]
	v_pk_fma_f32 v[112:113], v[138:139], v[42:43], v[56:57]
	v_pk_mul_f32 v[42:43], v[66:67], v[148:149] op_sel_hi:[0,1]
	v_pk_fma_f32 v[20:21], v[122:123], v[2:3], v[4:5]
	v_pk_mul_f32 v[2:3], v[66:67], v[166:167] op_sel_hi:[0,1]
	v_pk_mul_f32 v[8:9], v[66:67], v[156:157] op_sel_hi:[0,1]
	s_waitcnt vmcnt(0)
	v_pk_fma_f32 v[114:115], v[42:43], v[140:141], v[50:51]
	v_pk_mul_f32 v[42:43], v[66:67], v[144:145] op_sel_hi:[0,1]
	v_pk_fma_f32 v[2:3], v[128:129], v[2:3], v[46:47]
	v_pk_mul_f32 v[4:5], v[66:67], v[162:163] op_sel_hi:[0,1]
	v_pk_fma_f32 v[8:9], v[134:135], v[8:9], v[44:45]
	v_pk_fma_f32 v[116:117], v[42:43], v[142:143], v[52:53]
	v_lshl_add_u64 v[46:47], v[106:107], 0, s[24:25]
	v_cvt_pk_bf16_f32 v42, v68, v69
	v_cvt_pk_bf16_f32 v43, v78, v79
	v_cvt_pk_bf16_f32 v44, v80, v81
	v_cvt_pk_bf16_f32 v45, v90, v91
	v_pk_fma_f32 v[4:5], v[130:131], v[4:5], v[48:49]
	global_store_dwordx4 v[46:47], v[42:45], off nt
	v_lshl_add_u64 v[66:67], s[30:31], 0, v[100:101]
	v_add_co_u32_e32 v92, vcc, s45, v66
	v_cvt_pk_bf16_f32 v42, v22, v23
	v_cvt_pk_bf16_f32 v43, v24, v25
	v_cvt_pk_bf16_f32 v44, v18, v19
	v_cvt_pk_bf16_f32 v45, v20, v21
	global_store_dwordx4 v[46:47], v[42:45], off offset:1024 nt
	v_addc_co_u32_e32 v93, vcc, 0, v67, vcc
	s_nop 0
	v_cvt_pk_bf16_f32 v42, v2, v3
	v_cvt_pk_bf16_f32 v43, v4, v5
	v_cvt_pk_bf16_f32 v44, v6, v7
	v_cvt_pk_bf16_f32 v45, v8, v9
	global_store_dwordx4 v[46:47], v[42:45], off offset:2048 nt
	v_lshl_add_u64 v[94:95], v[66:67], 0, s[12:13]
	v_pk_mul_f32 v[96:97], v[68:69], v[68:69]
	v_cvt_pk_bf16_f32 v42, v110, v111
	v_cvt_pk_bf16_f32 v43, v112, v113
	v_cvt_pk_bf16_f32 v44, v114, v115
	v_cvt_pk_bf16_f32 v45, v116, v117
	global_store_dwordx4 v[46:47], v[42:45], off offset:3072 nt
	global_load_dwordx4 v[42:45], v100, s[30:31]
	s_nop 0
	global_load_dwordx4 v[46:49], v[92:93], off offset:-4096
	global_load_dwordx4 v[50:53], v100, s[30:31] offset:16
	global_load_dwordx4 v[54:57], v[94:95], off offset:16
	v_pk_mul_f32 v[120:121], v[78:79], v[78:79]
	v_add_f32_e32 v96, v96, v97
	v_add_f32_e32 v96, v120, v96
	v_pk_mul_f32 v[122:123], v[80:81], v[80:81]
	v_add_f32_e32 v96, v121, v96
	v_add_f32_e32 v96, v122, v96
	v_pk_mul_f32 v[124:125], v[90:91], v[90:91]
	v_add_f32_e32 v96, v123, v96
	v_add_f32_e32 v96, v124, v96
	v_pk_mul_f32 v[126:127], v[22:23], v[22:23]
	v_add_f32_e32 v96, v125, v96
	v_add_f32_e32 v96, v126, v96
	v_pk_mul_f32 v[128:129], v[24:25], v[24:25]
	v_add_f32_e32 v96, v127, v96
	v_add_f32_e32 v96, v128, v96
	v_pk_mul_f32 v[130:131], v[18:19], v[18:19]
	v_add_f32_e32 v96, v129, v96
	v_add_f32_e32 v96, v130, v96
	v_pk_mul_f32 v[132:133], v[20:21], v[20:21]
	v_add_f32_e32 v96, v131, v96
	v_add_f32_e32 v96, v132, v96
	v_pk_mul_f32 v[134:135], v[2:3], v[2:3]
	v_add_f32_e32 v96, v133, v96
	v_add_f32_e32 v96, v134, v96
	v_pk_mul_f32 v[136:137], v[4:5], v[4:5]
	v_add_f32_e32 v96, v135, v96
	v_add_f32_e32 v96, v136, v96
	v_pk_mul_f32 v[138:139], v[6:7], v[6:7]
	v_add_f32_e32 v96, v137, v96
	v_add_f32_e32 v96, v138, v96
	v_pk_mul_f32 v[140:141], v[8:9], v[8:9]
	v_add_f32_e32 v96, v139, v96
	v_add_f32_e32 v96, v140, v96
	v_pk_mul_f32 v[142:143], v[110:111], v[110:111]
	v_add_f32_e32 v96, v141, v96
	v_add_f32_e32 v96, v142, v96
	v_pk_mul_f32 v[144:145], v[112:113], v[112:113]
	v_add_f32_e32 v96, v143, v96
	v_add_f32_e32 v96, v144, v96
	v_pk_mul_f32 v[146:147], v[114:115], v[114:115]
	v_add_f32_e32 v96, v145, v96
	v_add_f32_e32 v96, v146, v96
	v_pk_mul_f32 v[148:149], v[116:117], v[116:117]
	v_add_f32_e32 v96, v147, v96
	v_add_f32_e32 v96, v148, v96
	v_add_f32_e32 v96, v149, v96
	v_mov_b32_e32 v97, v101
	v_lshl_add_u64 v[138:139], v[108:109], 0, s[24:25]
	v_add_f32_dpp v96, v96, v96 row_shr:1 row_mask:0xf bank_mask:0xf bound_ctrl:1
	s_and_b64 s[26:27], s[26:27], s[28:29]
	s_mov_b32 s24, s6
	v_add_f32_dpp v96, v96, v96 row_shr:2 row_mask:0xf bank_mask:0xf bound_ctrl:1
	s_add_i32 s41, s41, s42
	s_add_i32 s40, s40, s33
	v_add_f32_dpp v96, v96, v96 row_shr:4 row_mask:0xf bank_mask:0xf bound_ctrl:1
	s_add_i32 s36, s36, 1
	s_nop 0
	v_add_f32_dpp v96, v96, v96 row_shr:8 row_mask:0xf bank_mask:0xf bound_ctrl:1
	s_nop 1
	v_mov_b32_dpp v97, v96 row_bcast:15 row_mask:0xa bank_mask:0xf
	v_add_f32_e32 v96, v96, v97
	v_mov_b32_e32 v97, v101
	s_nop 1
	v_mov_b32_dpp v97, v96 row_bcast:31 row_mask:0xc bank_mask:0xf
	v_add_f32_e32 v96, v96, v97
	s_nop 0
	v_readlane_b32 s34, v96, 63
	s_nop 1
	v_fma_f32 v96, s34, v119, v1
	v_mul_f32_e32 v97, 0x4b800000, v96
	v_cmp_gt_f32_e32 vcc, s44, v96
	s_nop 1
	v_cndmask_b32_e32 v96, v96, v97, vcc
	v_rsq_f32_e32 v96, v96
	s_nop 0
	v_mul_f32_e32 v97, 0x45800000, v96
	v_cndmask_b32_e32 v136, v96, v97, vcc
	v_pk_mul_f32 v[68:69], v[68:69], v[136:137] op_sel_hi:[1,0]
	v_pk_mul_f32 v[22:23], v[22:23], v[136:137] op_sel_hi:[1,0]
	s_waitcnt vmcnt(2)
; __device__ __forceinline__ vu4 pack8(const float (&f)[8]) { vu4 w; w.x = pg8::cvt_pk_bf16(f[0], f[1]); w.y = pg8::cvt_pk_bf16(f[2], f[3]); w.z = pg8::cvt_pk_bf16(f[4], f[5]); w.w = pg8::cvt_pk_bf16(f[6], f[7]); return w; }
; template <bool XSRC_BF, bool XDST_BF> ...
;     ...
;         float xv[4][8]; vu4 hraw[4];
; #pragma unroll
;         for (int j = 0; j < 4; ++j) { if (XSRC_BF) unpack8(nxb[j], xv[j]); else {
; #pragma unroll
;                 for (int e = 0; e < 8; ++e) xv[j][e] = nxf[j][e]; }
;             hraw[j] = nho[j]; }
;         rown = it + 1 < niter ? ROW_OF(it + 1) : -1;
;         if (rown >= 0) ROW_LOAD(rown)
;     ...
; #pragma unroll
;             for (int j = 0; j < 4; ++j) { float sh[8], sc[8], o[8]; load8f(mpre + (size_t)b * 12288 + 8 * lane + 512 * j, sh); load8f(mpre + (size_t)b * 12288 + 2048 + 8 * lane + 512 * j, sc);
; #pragma unroll
;                 for (int e = 0; e < 8; ++e) o[e] = xv[j][e] * r2 * sc[e] + sh[e];
;                 if (ug) { const int col = 8 * lane + 512 * j; *(vu4*)(ug + ((size_t)((col >> 4) * 1280 + (row >> 5))) * 768 + (row & 31) * 16 + (col & 8)) = pack8(o); }
;                 else *(vu4*)(h + (size_t)row * DM + 8 * lane + 512 * j) = pack8(o); }
	v_pk_fma_f32 v[42:43], v[46:47], v[68:69], v[42:43]
	v_pk_mul_f32 v[46:47], v[78:79], v[136:137] op_sel_hi:[1,0]
	v_cvt_pk_bf16_f32 v42, v42, v43
	v_pk_fma_f32 v[44:45], v[48:49], v[46:47], v[44:45]
	v_pk_mul_f32 v[46:47], v[80:81], v[136:137] op_sel_hi:[1,0]
	v_pk_mul_f32 v[48:49], v[90:91], v[136:137] op_sel_hi:[1,0]
	s_waitcnt vmcnt(0)
	v_pk_fma_f32 v[46:47], v[54:55], v[46:47], v[50:51]
	v_pk_fma_f32 v[48:49], v[56:57], v[48:49], v[52:53]
	v_cvt_pk_bf16_f32 v43, v44, v45
	v_cvt_pk_bf16_f32 v44, v46, v47
	v_cvt_pk_bf16_f32 v45, v48, v49
	global_store_dwordx4 v[138:139], v[42:45], off
	global_load_dwordx4 v[42:45], v[94:95], off offset:2048
	s_nop 0
	global_load_dwordx4 v[46:49], v100, s[30:31] offset:2048
	global_load_dwordx4 v[50:53], v100, s[30:31] offset:2064
	global_load_dwordx4 v[54:57], v[94:95], off offset:2064
	v_pk_mul_f32 v[18:19], v[18:19], v[136:137] op_sel_hi:[1,0]
	v_pk_mul_f32 v[24:25], v[24:25], v[136:137] op_sel_hi:[1,0]
	v_pk_mul_f32 v[2:3], v[2:3], v[136:137] op_sel_hi:[1,0]
	v_pk_mul_f32 v[4:5], v[4:5], v[136:137] op_sel_hi:[1,0]
	v_pk_mul_f32 v[6:7], v[6:7], v[136:137] op_sel_hi:[1,0]
	v_pk_mul_f32 v[8:9], v[8:9], v[136:137] op_sel_hi:[1,0]
	v_mov_b64_e32 v[80:81], v[76:77]
	v_mov_b64_e32 v[96:97], v[88:89]
	v_mov_b64_e32 v[78:79], v[74:75]
	v_mov_b64_e32 v[94:95], v[86:87]
	s_waitcnt vmcnt(2)
	v_pk_fma_f32 v[22:23], v[22:23], v[42:43], v[46:47]
	v_pk_fma_f32 v[24:25], v[24:25], v[44:45], v[48:49]
	s_waitcnt vmcnt(0)
	v_pk_fma_f32 v[42:43], v[18:19], v[54:55], v[50:51]
	v_pk_mul_f32 v[18:19], v[20:21], v[136:137] op_sel_hi:[1,0]
	v_cvt_pk_bf16_f32 v20, v42, v43
	v_pk_fma_f32 v[44:45], v[18:19], v[56:57], v[52:53]
	v_cvt_pk_bf16_f32 v18, v22, v23
	v_cvt_pk_bf16_f32 v19, v24, v25
	v_cvt_pk_bf16_f32 v21, v44, v45
	v_add_co_u32_e32 v50, vcc, s43, v66
	global_store_dwordx4 v[138:139], v[18:21], off offset:1024
	v_lshl_add_u64 v[22:23], v[66:67], 0, s[8:9]
	v_addc_co_u32_e32 v51, vcc, 0, v67, vcc
	v_lshl_add_u64 v[46:47], v[66:67], 0, s[14:15]
	global_load_dwordx4 v[18:21], v[50:51], off
	s_nop 0
	global_load_dwordx4 v[22:25], v[22:23], off offset:16
	s_nop 0
	global_load_dwordx4 v[42:45], v[92:93], off
	v_lshl_add_u64 v[52:53], v[66:67], 0, s[10:11]
	global_load_dwordx4 v[46:49], v[46:47], off offset:16
	v_lshl_add_u64 v[54:55], v[66:67], 0, s[16:17]
	v_mov_b64_e32 v[66:67], v[70:71]
	v_mov_b64_e32 v[68:69], v[72:73]
	s_and_b64 vcc, exec, s[26:27]
	v_mov_b32_e32 v56, v60
	v_mov_b32_e32 v57, v61
	s_waitcnt vmcnt(1)
	v_pk_fma_f32 v[2:3], v[2:3], v[42:43], v[18:19]
	v_pk_fma_f32 v[4:5], v[4:5], v[44:45], v[20:21]
	s_waitcnt vmcnt(0)
	v_pk_fma_f32 v[6:7], v[6:7], v[46:47], v[22:23]
	v_pk_fma_f32 v[8:9], v[8:9], v[48:49], v[24:25]
	v_cvt_pk_bf16_f32 v2, v2, v3
	v_cvt_pk_bf16_f32 v3, v4, v5
	v_cvt_pk_bf16_f32 v4, v6, v7
	v_cvt_pk_bf16_f32 v5, v8, v9
	global_store_dwordx4 v[138:139], v[2:5], off offset:2048
	global_load_dwordx4 v[120:123], v[92:93], off offset:2048
	global_load_dwordx4 v[124:127], v[50:51], off offset:2048
	global_load_dwordx4 v[128:131], v[52:53], off offset:16
	global_load_dwordx4 v[132:135], v[54:55], off offset:16
	v_mov_b32_e32 v8, v16
	v_mov_b32_e32 v9, v17
	v_mov_b32_e32 v6, v14
	v_mov_b32_e32 v7, v15
	v_mov_b32_e32 v24, v12
	v_mov_b32_e32 v25, v13
	v_mov_b32_e32 v22, v10
	v_mov_b32_e32 v23, v11
	v_pk_mul_f32 v[10:11], v[110:111], v[136:137] op_sel_hi:[1,0]
	v_pk_mul_f32 v[12:13], v[112:113], v[136:137] op_sel_hi:[1,0]
	v_pk_mul_f32 v[14:15], v[114:115], v[136:137] op_sel_hi:[1,0]
	v_pk_mul_f32 v[16:17], v[116:117], v[136:137] op_sel_hi:[1,0]
	v_mov_b64_e32 v[92:93], v[84:85]
	v_mov_b64_e32 v[90:91], v[82:83]
	v_mov_b32_e32 v4, v36
	v_mov_b32_e32 v5, v37
	v_mov_b32_e32 v2, v34
	v_mov_b32_e32 v3, v35
	v_mov_b32_e32 v20, v32
	v_mov_b32_e32 v21, v33
	v_mov_b32_e32 v18, v30
	v_mov_b32_e32 v19, v31
	v_mov_b32_e32 v52, v64
	v_mov_b32_e32 v53, v65
	v_mov_b32_e32 v50, v62
	v_mov_b32_e32 v51, v63
	v_mov_b32_e32 v54, v58
	v_mov_b32_e32 v55, v59
	v_mov_b32_e32 v44, v40
	v_mov_b32_e32 v45, v41
	v_mov_b32_e32 v42, v38
	v_mov_b32_e32 v43, v39
	v_mov_b32_e32 v48, v28
	v_mov_b32_e32 v49, v29
	v_mov_b32_e32 v46, v26
	v_mov_b32_e32 v47, v27
	s_waitcnt vmcnt(2)
	v_pk_fma_f32 v[10:11], v[10:11], v[120:121], v[124:125]
	v_pk_fma_f32 v[12:13], v[12:13], v[122:123], v[126:127]
	s_waitcnt vmcnt(0)
	v_pk_fma_f32 v[14:15], v[14:15], v[132:133], v[128:129]
	v_pk_fma_f32 v[16:17], v[16:17], v[134:135], v[130:131]
	v_cvt_pk_bf16_f32 v10, v10, v11
	v_cvt_pk_bf16_f32 v11, v12, v13
	v_cvt_pk_bf16_f32 v12, v14, v15
	v_cvt_pk_bf16_f32 v13, v16, v17
	global_store_dwordx4 v[138:139], v[10:13], off offset:3072
	s_cbranch_vccz .LBB0_878
